# weight-tile conversion (phase 3 convert_rest, phase 6 chores): the 16 per-row scale values loaded together and waited once instead of 16 loads each followed by a full vmcnt(0) drain
# speedup vs baseline: 1.0116x; 1.0116x over previous
; __device__ void wt_tile(const float* src, int ld, int k0, int n0, bf16_t* dst, int Kdst, const float* kscale, float mul, LAS float* tile, bool rotperm = false, int drow0 = -1) {
;     ...
;     for (int i = 0; i < 16; ++i) { const int k = (tid >> 7) + 4 * i, n = tid & 127; v[i] = src[(size_t)(k0 + k) * ld + n0 + n]; }
; #pragma unroll
;     for (int i = 0; i < 16; ++i) { const int k = (tid >> 7) + 4 * i, n = tid & 127; float x = v[i] * mul; if (kscale) x *= kscale[k0 + k]; tile[k * 129 + n] = x; }
.LBB0_419:
	s_andn2_b64 vcc, exec, s[6:7]
	s_cbranch_vccnz .LBB0_453
	s_add_i32 s6, s8, 0xfffffe20
	v_readlane_b32 s40, v254, 50
	s_lshr_b32 s6, s6, 4
	v_readlane_b32 s44, v254, 54
	v_readlane_b32 s45, v254, 55
	v_readlane_b32 s46, v254, 56
	v_readlane_b32 s47, v254, 57
	v_readlane_b32 s48, v254, 58
	v_readlane_b32 s49, v254, 59
	v_readlane_b32 s50, v254, 60
	v_readlane_b32 s51, v254, 61
	s_lshl_b32 s38, s6, 7
	v_readlane_b32 s52, v254, 62
	v_readlane_b32 s53, v254, 63
	v_readlane_b32 s54, v255, 0
	v_readlane_b32 s55, v255, 1
	s_mov_b64 s[44:45], s[48:49]
	s_and_b32 s7, s15, 0x3c0
	v_mov_b32_e32 v4, v162
	s_lshl_b64 s[34:35], s[38:39], 2
	s_mov_b64 s[46:47], s[50:51]
	s_mov_b64 s[48:49], s[52:53]
	s_mov_b64 s[50:51], s[54:55]
	s_add_u32 s34, s50, s34
	v_and_b32_e32 v15, 0x7f, v4
	v_ashrrev_i32_e32 v11, 7, v4
	s_addc_u32 s35, s51, s35
	v_lshlrev_b32_e32 v0, 2, v15
	v_add_u32_e32 v2, s7, v11
	s_waitcnt vmcnt(0)
	v_lshl_add_u64 v[22:23], s[34:35], 0, v[0:1]
	v_mad_i64_i32 v[6:7], s[34:35], v2, s95, v[22:23]
	v_add_u32_e32 v0, 4, v2
	global_load_dword v21, v[6:7], off
	v_mad_i64_i32 v[6:7], s[34:35], v0, s95, v[22:23]
	v_add_u32_e32 v0, 8, v2
	global_load_dword v20, v[6:7], off
	v_mad_i64_i32 v[6:7], s[34:35], v0, s95, v[22:23]
	v_add_u32_e32 v0, 12, v2
	global_load_dword v19, v[6:7], off
	v_mad_i64_i32 v[6:7], s[34:35], v0, s95, v[22:23]
	v_add_u32_e32 v0, 16, v2
	global_load_dword v18, v[6:7], off
	v_mad_i64_i32 v[6:7], s[34:35], v0, s95, v[22:23]
	v_add_u32_e32 v0, 20, v2
	global_load_dword v16, v[6:7], off
	v_mad_i64_i32 v[6:7], s[34:35], v0, s95, v[22:23]
	v_add_u32_e32 v0, 24, v2
	global_load_dword v14, v[6:7], off
	v_mad_i64_i32 v[6:7], s[34:35], v0, s95, v[22:23]
	v_add_u32_e32 v0, 28, v2
	global_load_dword v12, v[6:7], off
	v_mad_i64_i32 v[6:7], s[34:35], v0, s95, v[22:23]
	v_add_u32_e32 v0, 32, v2
	global_load_dword v17, v[6:7], off
	v_mad_i64_i32 v[6:7], s[34:35], v0, s95, v[22:23]
	v_add_u32_e32 v0, 36, v2
	global_load_dword v13, v[6:7], off
	v_mad_i64_i32 v[6:7], s[34:35], v0, s95, v[22:23]
	v_add_u32_e32 v0, 40, v2
	global_load_dword v10, v[6:7], off
	v_mad_i64_i32 v[6:7], s[34:35], v0, s95, v[22:23]
	v_add_u32_e32 v0, 44, v2
	global_load_dword v9, v[6:7], off
	v_mad_i64_i32 v[6:7], s[34:35], v0, s95, v[22:23]
	v_add_u32_e32 v0, 48, v2
	global_load_dword v8, v[6:7], off
	v_mad_i64_i32 v[6:7], s[34:35], v0, s95, v[22:23]
	v_add_u32_e32 v0, 52, v2
	v_mad_i64_i32 v[24:25], s[34:35], v0, s95, v[22:23]
	v_add_u32_e32 v0, 56, v2
	v_add_u32_e32 v3, 60, v2
	global_load_dword v6, v[6:7], off
	v_readlane_b32 s41, v254, 51
	global_load_dword v5, v[24:25], off
	v_mad_i64_i32 v[24:25], s[34:35], v0, s95, v[22:23]
	v_mad_i64_i32 v[22:23], s[34:35], v3, s95, v[22:23]
	global_load_dword v0, v[24:25], off
	global_load_dword v7, v[22:23], off
	v_ashrrev_i32_e32 v3, 31, v2
	v_cndmask_b32_e64 v22, 0, 1, s[4:5]
	v_cmp_ne_u32_e64 s[40:41], 1, v22
	s_andn2_b64 vcc, exec, s[4:5]
	v_lshl_add_u64 v[2:3], v[2:3], 2, s[46:47]
	v_readlane_b32 s42, v254, 52
	v_readlane_b32 s43, v254, 53
	s_cbranch_vccnz .LBB0_422
	global_load_dword v130, v[2:3], off
	global_load_dword v131, v[2:3], off offset:16
	global_load_dword v132, v[2:3], off offset:32
	global_load_dword v133, v[2:3], off offset:48
	global_load_dword v134, v[2:3], off offset:64
	global_load_dword v135, v[2:3], off offset:80
	global_load_dword v136, v[2:3], off offset:96
	global_load_dword v137, v[2:3], off offset:112
	global_load_dword v138, v[2:3], off offset:128
	global_load_dword v139, v[2:3], off offset:144
	global_load_dword v140, v[2:3], off offset:160
	global_load_dword v141, v[2:3], off offset:176
	global_load_dword v142, v[2:3], off offset:192
	global_load_dword v143, v[2:3], off offset:208
	global_load_dword v144, v[2:3], off offset:224
	global_load_dword v145, v[2:3], off offset:240
	s_waitcnt vmcnt(0)
	v_mul_f32_e32 v21, v21, v130
.LBB0_422:
	s_movk_i32 s19, 0x204
	v_lshl_add_u32 v15, v15, 2, 0
	v_mul_lo_u32 v11, v11, s19
	v_add_u32_e32 v11, v15, v11
	s_and_b64 vcc, exec, s[40:41]
	s_waitcnt vmcnt(15)
	ds_write_b32 v11, v21
	s_cbranch_vccnz .LBB0_424
	v_mul_f32_e32 v20, v20, v131
.LBB0_424:
	s_and_b64 vcc, exec, s[40:41]
	s_waitcnt vmcnt(14)
	ds_write_b32 v11, v20 offset:2064
	s_cbranch_vccnz .LBB0_426
	v_mul_f32_e32 v19, v19, v132
.LBB0_426:
	s_and_b64 vcc, exec, s[40:41]
	s_waitcnt vmcnt(13)
	ds_write_b32 v11, v19 offset:4128
	s_cbranch_vccnz .LBB0_428
	v_mul_f32_e32 v18, v18, v133
.LBB0_428:
	s_and_b64 vcc, exec, s[40:41]
	s_waitcnt vmcnt(12)
	ds_write_b32 v11, v18 offset:6192
	s_cbranch_vccnz .LBB0_430
	v_mul_f32_e32 v16, v16, v134
.LBB0_430:
	s_and_b64 vcc, exec, s[40:41]
	s_waitcnt vmcnt(11)
	ds_write_b32 v11, v16 offset:8256
	s_cbranch_vccnz .LBB0_432
	v_mul_f32_e32 v14, v14, v135
.LBB0_432:
	s_and_b64 vcc, exec, s[40:41]
	s_waitcnt vmcnt(10)
	ds_write_b32 v11, v14 offset:10320
	s_cbranch_vccnz .LBB0_434
	v_mul_f32_e32 v12, v12, v136
.LBB0_434:
	s_and_b64 vcc, exec, s[40:41]
	s_waitcnt vmcnt(9)
	ds_write_b32 v11, v12 offset:12384
	s_cbranch_vccnz .LBB0_436
	v_mul_f32_e32 v17, v17, v137
.LBB0_436:
	s_and_b64 vcc, exec, s[40:41]
	s_waitcnt vmcnt(8)
	ds_write_b32 v11, v17 offset:14448
	s_cbranch_vccnz .LBB0_438
	v_mul_f32_e32 v13, v13, v138
.LBB0_438:
	s_and_b64 vcc, exec, s[40:41]
	s_waitcnt vmcnt(7)
	ds_write_b32 v11, v13 offset:16512
	s_cbranch_vccnz .LBB0_440
	v_mul_f32_e32 v10, v10, v139
.LBB0_440:
	s_and_b64 vcc, exec, s[40:41]
	s_waitcnt vmcnt(6)
	ds_write_b32 v11, v10 offset:18576
	s_cbranch_vccnz .LBB0_442
	v_mul_f32_e32 v9, v9, v140
.LBB0_442:
	s_and_b64 vcc, exec, s[40:41]
	s_waitcnt vmcnt(5)
	ds_write_b32 v11, v9 offset:20640
	s_cbranch_vccnz .LBB0_444
	v_mul_f32_e32 v8, v8, v141
.LBB0_444:
	s_and_b64 vcc, exec, s[40:41]
	s_waitcnt vmcnt(4)
	ds_write_b32 v11, v8 offset:22704
	s_cbranch_vccnz .LBB0_446
	v_mul_f32_e32 v6, v6, v142
.LBB0_446:
	s_and_b64 vcc, exec, s[40:41]
	s_waitcnt vmcnt(3)
	ds_write_b32 v11, v6 offset:24768
	s_cbranch_vccnz .LBB0_448
	v_mul_f32_e32 v5, v5, v143
.LBB0_448:
	s_and_b64 vcc, exec, s[40:41]
	s_waitcnt vmcnt(2)
	ds_write_b32 v11, v5 offset:26832
	s_cbranch_vccnz .LBB0_450
	v_mul_f32_e32 v0, v0, v144
.LBB0_450:
	s_and_b64 vcc, exec, s[40:41]
	s_waitcnt vmcnt(1)
	ds_write_b32 v11, v0 offset:28896
	s_cbranch_vccnz .LBB0_452
	v_mul_f32_e32 v7, v7, v145

; __device__ void wt_tile(const float* src, int ld, int k0, int n0, bf16_t* dst, int Kdst, const float* kscale, float mul, LAS float* tile, bool rotperm = false, int drow0 = -1) {
;     ...
;     for (int i = 0; i < 16; ++i) { const int k = (tid >> 7) + 4 * i, n = tid & 127; v[i] = src[(size_t)(k0 + k) * ld + n0 + n]; }
; #pragma unroll
;     for (int i = 0; i < 16; ++i) { const int k = (tid >> 7) + 4 * i, n = tid & 127; float x = v[i] * mul; if (kscale) x *= kscale[k0 + k]; tile[k * 129 + n] = x; }
.LBB0_454:
	s_andn2_b64 vcc, exec, s[6:7]
	s_cbranch_vccnz .LBB0_488
	s_add_i32 s6, s8, 0xffffff80
	v_readlane_b32 s40, v254, 50
	s_lshr_b32 s6, s6, 4
	v_readlane_b32 s44, v254, 54
	v_readlane_b32 s45, v254, 55
	v_readlane_b32 s46, v254, 56
	v_readlane_b32 s47, v254, 57
	v_readlane_b32 s48, v254, 58
	v_readlane_b32 s49, v254, 59
	v_readlane_b32 s50, v254, 60
	v_readlane_b32 s51, v254, 61
	s_lshl_b32 s38, s6, 7
	v_readlane_b32 s52, v254, 62
	v_readlane_b32 s53, v254, 63
	v_readlane_b32 s54, v255, 0
	v_readlane_b32 s55, v255, 1
	s_mov_b64 s[44:45], s[48:49]
	s_and_b32 s7, s15, 0x3c0
	v_mov_b32_e32 v4, v162
	s_lshl_b64 s[34:35], s[38:39], 2
	s_mov_b64 s[46:47], s[50:51]
	s_mov_b64 s[48:49], s[52:53]
	s_add_u32 s34, s48, s34
	v_and_b32_e32 v15, 0x7f, v4
	v_ashrrev_i32_e32 v11, 7, v4
	s_addc_u32 s35, s49, s35
	v_lshlrev_b32_e32 v0, 2, v15
	v_add_u32_e32 v2, s7, v11
	s_waitcnt vmcnt(0)
	v_lshl_add_u64 v[22:23], s[34:35], 0, v[0:1]
	v_mad_i64_i32 v[6:7], s[34:35], v2, s95, v[22:23]
	v_add_u32_e32 v0, 4, v2
	global_load_dword v21, v[6:7], off
	v_mad_i64_i32 v[6:7], s[34:35], v0, s95, v[22:23]
	v_add_u32_e32 v0, 8, v2
	global_load_dword v20, v[6:7], off
	v_mad_i64_i32 v[6:7], s[34:35], v0, s95, v[22:23]
	v_add_u32_e32 v0, 12, v2
	global_load_dword v19, v[6:7], off
	v_mad_i64_i32 v[6:7], s[34:35], v0, s95, v[22:23]
	v_add_u32_e32 v0, 16, v2
	global_load_dword v18, v[6:7], off
	v_mad_i64_i32 v[6:7], s[34:35], v0, s95, v[22:23]
	v_add_u32_e32 v0, 20, v2
	global_load_dword v16, v[6:7], off
	v_mad_i64_i32 v[6:7], s[34:35], v0, s95, v[22:23]
	v_add_u32_e32 v0, 24, v2
	global_load_dword v14, v[6:7], off
	v_mad_i64_i32 v[6:7], s[34:35], v0, s95, v[22:23]
	v_add_u32_e32 v0, 28, v2
	global_load_dword v12, v[6:7], off
	v_mad_i64_i32 v[6:7], s[34:35], v0, s95, v[22:23]
	v_add_u32_e32 v0, 32, v2
	global_load_dword v17, v[6:7], off
	v_mad_i64_i32 v[6:7], s[34:35], v0, s95, v[22:23]
	v_add_u32_e32 v0, 36, v2
	global_load_dword v13, v[6:7], off
	v_mad_i64_i32 v[6:7], s[34:35], v0, s95, v[22:23]
	v_add_u32_e32 v0, 40, v2
	global_load_dword v10, v[6:7], off
	v_mad_i64_i32 v[6:7], s[34:35], v0, s95, v[22:23]
	v_add_u32_e32 v0, 44, v2
	global_load_dword v9, v[6:7], off
	v_mad_i64_i32 v[6:7], s[34:35], v0, s95, v[22:23]
	v_add_u32_e32 v0, 48, v2
	global_load_dword v8, v[6:7], off
	v_mad_i64_i32 v[6:7], s[34:35], v0, s95, v[22:23]
	v_add_u32_e32 v0, 52, v2
	v_mad_i64_i32 v[24:25], s[34:35], v0, s95, v[22:23]
	v_add_u32_e32 v0, 56, v2
	v_add_u32_e32 v3, 60, v2
	global_load_dword v6, v[6:7], off
	v_readlane_b32 s41, v254, 51
	global_load_dword v5, v[24:25], off
	v_mad_i64_i32 v[24:25], s[34:35], v0, s95, v[22:23]
	v_mad_i64_i32 v[22:23], s[34:35], v3, s95, v[22:23]
	global_load_dword v0, v[24:25], off
	global_load_dword v7, v[22:23], off
	v_ashrrev_i32_e32 v3, 31, v2
	v_cndmask_b32_e64 v22, 0, 1, s[4:5]
	v_cmp_ne_u32_e64 s[40:41], 1, v22
	s_andn2_b64 vcc, exec, s[4:5]
	v_lshl_add_u64 v[2:3], v[2:3], 2, s[46:47]
	v_readlane_b32 s42, v254, 52
	v_readlane_b32 s43, v254, 53
	s_mov_b64 s[50:51], s[54:55]
	s_cbranch_vccnz .LBB0_457
	global_load_dword v130, v[2:3], off
	global_load_dword v131, v[2:3], off offset:16
	global_load_dword v132, v[2:3], off offset:32
	global_load_dword v133, v[2:3], off offset:48
	global_load_dword v134, v[2:3], off offset:64
	global_load_dword v135, v[2:3], off offset:80
	global_load_dword v136, v[2:3], off offset:96
	global_load_dword v137, v[2:3], off offset:112
	global_load_dword v138, v[2:3], off offset:128
	global_load_dword v139, v[2:3], off offset:144
	global_load_dword v140, v[2:3], off offset:160
	global_load_dword v141, v[2:3], off offset:176
	global_load_dword v142, v[2:3], off offset:192
	global_load_dword v143, v[2:3], off offset:208
	global_load_dword v144, v[2:3], off offset:224
	global_load_dword v145, v[2:3], off offset:240
	s_waitcnt vmcnt(0)
	v_mul_f32_e32 v21, v21, v130

; __device__ void wt_tile(const float* src, int ld, int k0, int n0, bf16_t* dst, int Kdst, const float* kscale, float mul, LAS float* tile, bool rotperm = false, int drow0 = -1) {
;     ...
;     for (int i = 0; i < 16; ++i) { const int k = (tid >> 7) + 4 * i, n = tid & 127; v[i] = src[(size_t)(k0 + k) * ld + n0 + n]; }
; #pragma unroll
;     for (int i = 0; i < 16; ++i) { const int k = (tid >> 7) + 4 * i, n = tid & 127; float x = v[i] * mul; if (kscale) x *= kscale[k0 + k]; tile[k * 129 + n] = x; }
.LBB0_500:
	s_andn2_b64 vcc, exec, s[4:5]
	s_cbranch_vccnz .LBB0_534
	s_add_i32 s4, s15, 0xfffffe20
	v_readlane_b32 s40, v254, 50
	s_lshr_b32 s4, s4, 4
	v_readlane_b32 s44, v254, 54
	v_readlane_b32 s45, v254, 55
	v_readlane_b32 s46, v254, 56
	v_readlane_b32 s47, v254, 57
	v_readlane_b32 s48, v254, 58
	v_readlane_b32 s49, v254, 59
	v_readlane_b32 s50, v254, 60
	v_readlane_b32 s51, v254, 61
	s_lshl_b32 s38, s4, 7
	v_readlane_b32 s52, v254, 62
	v_readlane_b32 s53, v254, 63
	v_readlane_b32 s54, v255, 0
	v_readlane_b32 s55, v255, 1
	s_mov_b64 s[44:45], s[48:49]
	s_and_b32 s5, s11, 0x3c0
	v_mov_b32_e32 v4, v162
	s_lshl_b64 s[16:17], s[38:39], 2
	s_mov_b64 s[46:47], s[50:51]
	s_mov_b64 s[48:49], s[52:53]
	s_mov_b64 s[50:51], s[54:55]
	s_add_u32 s16, s50, s16
	v_and_b32_e32 v15, 0x7f, v4
	v_ashrrev_i32_e32 v11, 7, v4
	s_addc_u32 s17, s51, s17
	v_lshlrev_b32_e32 v0, 2, v15
	v_add_u32_e32 v2, s5, v11
	s_waitcnt vmcnt(0)
	v_lshl_add_u64 v[22:23], s[16:17], 0, v[0:1]
	v_mad_i64_i32 v[6:7], s[16:17], v2, s95, v[22:23]
	v_add_u32_e32 v0, 4, v2
	global_load_dword v21, v[6:7], off
	v_mad_i64_i32 v[6:7], s[16:17], v0, s95, v[22:23]
	v_add_u32_e32 v0, 8, v2
	global_load_dword v20, v[6:7], off
	v_mad_i64_i32 v[6:7], s[16:17], v0, s95, v[22:23]
	v_add_u32_e32 v0, 12, v2
	global_load_dword v19, v[6:7], off
	v_mad_i64_i32 v[6:7], s[16:17], v0, s95, v[22:23]
	v_add_u32_e32 v0, 16, v2
	global_load_dword v18, v[6:7], off
	v_mad_i64_i32 v[6:7], s[16:17], v0, s95, v[22:23]
	v_add_u32_e32 v0, 20, v2
	global_load_dword v16, v[6:7], off
	v_mad_i64_i32 v[6:7], s[16:17], v0, s95, v[22:23]
	v_add_u32_e32 v0, 24, v2
	global_load_dword v14, v[6:7], off
	v_mad_i64_i32 v[6:7], s[16:17], v0, s95, v[22:23]
	v_add_u32_e32 v0, 28, v2
	global_load_dword v12, v[6:7], off
	v_mad_i64_i32 v[6:7], s[16:17], v0, s95, v[22:23]
	v_add_u32_e32 v0, 32, v2
	global_load_dword v17, v[6:7], off
	v_mad_i64_i32 v[6:7], s[16:17], v0, s95, v[22:23]
	v_add_u32_e32 v0, 36, v2
	global_load_dword v13, v[6:7], off
	v_mad_i64_i32 v[6:7], s[16:17], v0, s95, v[22:23]
	v_add_u32_e32 v0, 40, v2
	global_load_dword v10, v[6:7], off
	v_mad_i64_i32 v[6:7], s[16:17], v0, s95, v[22:23]
	v_add_u32_e32 v0, 44, v2
	global_load_dword v9, v[6:7], off
	v_mad_i64_i32 v[6:7], s[16:17], v0, s95, v[22:23]
	v_add_u32_e32 v0, 48, v2
	global_load_dword v8, v[6:7], off
	v_mad_i64_i32 v[6:7], s[16:17], v0, s95, v[22:23]
	v_add_u32_e32 v0, 52, v2
	v_mad_i64_i32 v[24:25], s[16:17], v0, s95, v[22:23]
	v_add_u32_e32 v0, 56, v2
	v_add_u32_e32 v3, 60, v2
	global_load_dword v6, v[6:7], off
	v_readlane_b32 s41, v254, 51
	global_load_dword v5, v[24:25], off
	v_mad_i64_i32 v[24:25], s[16:17], v0, s95, v[22:23]
	v_mad_i64_i32 v[22:23], s[16:17], v3, s95, v[22:23]
	global_load_dword v0, v[24:25], off
	global_load_dword v7, v[22:23], off
	v_ashrrev_i32_e32 v3, 31, v2
	v_cndmask_b32_e64 v22, 0, 1, s[2:3]
	v_cmp_ne_u32_e64 s[40:41], 1, v22
	s_andn2_b64 vcc, exec, s[2:3]
	v_lshl_add_u64 v[2:3], v[2:3], 2, s[46:47]
	v_readlane_b32 s42, v254, 52
	v_readlane_b32 s43, v254, 53
	s_cbranch_vccnz .LBB0_503
	global_load_dword v130, v[2:3], off
	global_load_dword v131, v[2:3], off offset:16
	global_load_dword v132, v[2:3], off offset:32
	global_load_dword v133, v[2:3], off offset:48
	global_load_dword v134, v[2:3], off offset:64
	global_load_dword v135, v[2:3], off offset:80
	global_load_dword v136, v[2:3], off offset:96
	global_load_dword v137, v[2:3], off offset:112
	global_load_dword v138, v[2:3], off offset:128
	global_load_dword v139, v[2:3], off offset:144
	global_load_dword v140, v[2:3], off offset:160
	global_load_dword v141, v[2:3], off offset:176
	global_load_dword v142, v[2:3], off offset:192
	global_load_dword v143, v[2:3], off offset:208
	global_load_dword v144, v[2:3], off offset:224
	global_load_dword v145, v[2:3], off offset:240
	s_waitcnt vmcnt(0)
	v_mul_f32_e32 v21, v21, v130
.LBB0_503:
	s_movk_i32 s16, 0x204
	v_lshl_add_u32 v15, v15, 2, 0
	v_mul_lo_u32 v11, v11, s16
	v_add_u32_e32 v11, v15, v11
	s_and_b64 vcc, exec, s[40:41]
	s_waitcnt vmcnt(15)
	ds_write_b32 v11, v21
	s_cbranch_vccnz .LBB0_505
	v_mul_f32_e32 v20, v20, v131

; __device__ void wt_tile(const float* src, int ld, int k0, int n0, bf16_t* dst, int Kdst, const float* kscale, float mul, LAS float* tile, bool rotperm = false, int drow0 = -1) {
;     ...
;     for (int i = 0; i < 16; ++i) { const int k = (tid >> 7) + 4 * i, n = tid & 127; v[i] = src[(size_t)(k0 + k) * ld + n0 + n]; }
; #pragma unroll
;     for (int i = 0; i < 16; ++i) { const int k = (tid >> 7) + 4 * i, n = tid & 127; float x = v[i] * mul; if (kscale) x *= kscale[k0 + k]; tile[k * 129 + n] = x; }
.LBB0_535:
	s_andn2_b64 vcc, exec, s[4:5]
	s_cbranch_vccnz .LBB0_569
	s_add_i32 s4, s15, 0xffffff80
	v_readlane_b32 s40, v254, 50
	s_lshr_b32 s4, s4, 4
	v_readlane_b32 s44, v254, 54
	v_readlane_b32 s45, v254, 55
	v_readlane_b32 s46, v254, 56
	v_readlane_b32 s47, v254, 57
	v_readlane_b32 s48, v254, 58
	v_readlane_b32 s49, v254, 59
	v_readlane_b32 s50, v254, 60
	v_readlane_b32 s51, v254, 61
	s_lshl_b32 s38, s4, 7
	v_readlane_b32 s52, v254, 62
	v_readlane_b32 s53, v254, 63
	v_readlane_b32 s54, v255, 0
	v_readlane_b32 s55, v255, 1
	s_mov_b64 s[44:45], s[48:49]
	s_and_b32 s5, s11, 0x3c0
	v_mov_b32_e32 v4, v162
	s_lshl_b64 s[16:17], s[38:39], 2
	s_mov_b64 s[46:47], s[50:51]
	s_mov_b64 s[48:49], s[52:53]
	s_add_u32 s16, s48, s16
	v_and_b32_e32 v15, 0x7f, v4
	v_ashrrev_i32_e32 v11, 7, v4
	s_addc_u32 s17, s49, s17
	v_lshlrev_b32_e32 v0, 2, v15
	v_add_u32_e32 v2, s5, v11
	s_waitcnt vmcnt(0)
	v_lshl_add_u64 v[22:23], s[16:17], 0, v[0:1]
	v_mad_i64_i32 v[6:7], s[16:17], v2, s95, v[22:23]
	v_add_u32_e32 v0, 4, v2
	global_load_dword v21, v[6:7], off
	v_mad_i64_i32 v[6:7], s[16:17], v0, s95, v[22:23]
	v_add_u32_e32 v0, 8, v2
	global_load_dword v20, v[6:7], off
	v_mad_i64_i32 v[6:7], s[16:17], v0, s95, v[22:23]
	v_add_u32_e32 v0, 12, v2
	global_load_dword v19, v[6:7], off
	v_mad_i64_i32 v[6:7], s[16:17], v0, s95, v[22:23]
	v_add_u32_e32 v0, 16, v2
	global_load_dword v18, v[6:7], off
	v_mad_i64_i32 v[6:7], s[16:17], v0, s95, v[22:23]
	v_add_u32_e32 v0, 20, v2
	global_load_dword v16, v[6:7], off
	v_mad_i64_i32 v[6:7], s[16:17], v0, s95, v[22:23]
	v_add_u32_e32 v0, 24, v2
	global_load_dword v14, v[6:7], off
	v_mad_i64_i32 v[6:7], s[16:17], v0, s95, v[22:23]
	v_add_u32_e32 v0, 28, v2
	global_load_dword v12, v[6:7], off
	v_mad_i64_i32 v[6:7], s[16:17], v0, s95, v[22:23]
	v_add_u32_e32 v0, 32, v2
	global_load_dword v17, v[6:7], off
	v_mad_i64_i32 v[6:7], s[16:17], v0, s95, v[22:23]
	v_add_u32_e32 v0, 36, v2
	global_load_dword v13, v[6:7], off
	v_mad_i64_i32 v[6:7], s[16:17], v0, s95, v[22:23]
	v_add_u32_e32 v0, 40, v2
	global_load_dword v10, v[6:7], off
	v_mad_i64_i32 v[6:7], s[16:17], v0, s95, v[22:23]
	v_add_u32_e32 v0, 44, v2
	global_load_dword v9, v[6:7], off
	v_mad_i64_i32 v[6:7], s[16:17], v0, s95, v[22:23]
	v_add_u32_e32 v0, 48, v2
	global_load_dword v8, v[6:7], off
	v_mad_i64_i32 v[6:7], s[16:17], v0, s95, v[22:23]
	v_add_u32_e32 v0, 52, v2
	v_mad_i64_i32 v[24:25], s[16:17], v0, s95, v[22:23]
	v_add_u32_e32 v0, 56, v2
	v_add_u32_e32 v3, 60, v2
	global_load_dword v6, v[6:7], off
	v_readlane_b32 s41, v254, 51
	global_load_dword v5, v[24:25], off
	v_mad_i64_i32 v[24:25], s[16:17], v0, s95, v[22:23]
	v_mad_i64_i32 v[22:23], s[16:17], v3, s95, v[22:23]
	global_load_dword v0, v[24:25], off
	global_load_dword v7, v[22:23], off
	v_ashrrev_i32_e32 v3, 31, v2
	v_cndmask_b32_e64 v22, 0, 1, s[2:3]
	v_cmp_ne_u32_e64 s[40:41], 1, v22
	s_andn2_b64 vcc, exec, s[2:3]
	v_lshl_add_u64 v[2:3], v[2:3], 2, s[46:47]
	v_readlane_b32 s42, v254, 52
	v_readlane_b32 s43, v254, 53
	s_mov_b64 s[50:51], s[54:55]
	s_cbranch_vccnz .LBB0_538
	global_load_dword v130, v[2:3], off
	global_load_dword v131, v[2:3], off offset:16
	global_load_dword v132, v[2:3], off offset:32
	global_load_dword v133, v[2:3], off offset:48
	global_load_dword v134, v[2:3], off offset:64
	global_load_dword v135, v[2:3], off offset:80
	global_load_dword v136, v[2:3], off offset:96
	global_load_dword v137, v[2:3], off offset:112
	global_load_dword v138, v[2:3], off offset:128
	global_load_dword v139, v[2:3], off offset:144
	global_load_dword v140, v[2:3], off offset:160
	global_load_dword v141, v[2:3], off offset:176
	global_load_dword v142, v[2:3], off offset:192
	global_load_dword v143, v[2:3], off offset:208
	global_load_dword v144, v[2:3], off offset:224
	global_load_dword v145, v[2:3], off offset:240
	s_waitcnt vmcnt(0)
	v_mul_f32_e32 v21, v21, v130

; __device__ void wt_tile(const float* src, int ld, int k0, int n0, bf16_t* dst, int Kdst, const float* kscale, float mul, LAS float* tile, bool rotperm = false, int drow0 = -1) {
;     ...
;     for (int i = 0; i < 16; ++i) { const int k = (tid >> 7) + 4 * i, n = tid & 127; v[i] = src[(size_t)(k0 + k) * ld + n0 + n]; }
; #pragma unroll
;     for (int i = 0; i < 16; ++i) { const int k = (tid >> 7) + 4 * i, n = tid & 127; float x = v[i] * mul; if (kscale) x *= kscale[k0 + k]; tile[k * 129 + n] = x; }
.LBB0_989:
	s_andn2_b64 vcc, exec, s[4:5]
	s_cbranch_vccnz .LBB0_986
	v_readlane_b32 s40, v255, 2
	s_and_b32 s4, s15, 0xffffff80
	v_readlane_b32 s44, v255, 6
	v_readlane_b32 s45, v255, 7
	v_readlane_b32 s46, v255, 8
	v_readlane_b32 s47, v255, 9
	v_readlane_b32 s48, v255, 10
	v_readlane_b32 s49, v255, 11
	v_mov_b32_e32 v4, v162
	s_ashr_i32 s5, s4, 31
	v_readlane_b32 s50, v255, 12
	v_readlane_b32 s51, v255, 13
	s_mov_b64 s[44:45], s[48:49]
	s_and_b32 s17, s13, 0x3c0
	s_lshl_b64 s[18:19], s[4:5], 2
	v_ashrrev_i32_e32 v5, 7, v4
	s_mov_b64 s[46:47], s[50:51]
	v_and_b32_e32 v6, 0x7f, v4
	v_add_u32_e32 v2, s17, v5
	s_add_u32 s18, s46, s18
	s_addc_u32 s19, s47, s19
	v_lshlrev_b32_e32 v0, 2, v6
	s_waitcnt lgkmcnt(0)
	v_ashrrev_i32_e32 v3, 31, v2
	v_lshl_add_u64 v[8:9], s[18:19], 0, v[0:1]
	v_lshlrev_b64 v[10:11], 12, v[2:3]
	s_waitcnt vmcnt(0)
	v_lshl_add_u64 v[22:23], v[8:9], 0, v[10:11]
	v_add_co_u32_e32 v8, vcc, s24, v22
	s_mov_b32 s5, 0x8000
	s_nop 0
	v_addc_co_u32_e32 v9, vcc, 0, v23, vcc
	global_load_dword v21, v[22:23], off
	global_load_dword v20, v[8:9], off
	v_add_co_u32_e32 v8, vcc, s5, v22
	s_mov_b32 s5, 0xc000
	s_nop 0
	v_addc_co_u32_e32 v9, vcc, 0, v23, vcc
	global_load_dword v17, v[8:9], off
	v_add_co_u32_e32 v8, vcc, s5, v22
	s_mov_b32 s5, 0x10000
	s_nop 0
	v_addc_co_u32_e32 v9, vcc, 0, v23, vcc
	global_load_dword v16, v[8:9], off
	v_add_co_u32_e32 v8, vcc, s5, v22
	s_mov_b32 s5, 0x14000
	s_nop 0
	v_addc_co_u32_e32 v9, vcc, 0, v23, vcc
	global_load_dword v14, v[8:9], off
	v_add_co_u32_e32 v8, vcc, s5, v22
	s_mov_b32 s5, 0x18000
	s_nop 0
	v_addc_co_u32_e32 v9, vcc, 0, v23, vcc
	global_load_dword v11, v[8:9], off
	v_add_co_u32_e32 v8, vcc, s5, v22
	s_mov_b32 s5, 0x1c000
	s_nop 0
	v_addc_co_u32_e32 v9, vcc, 0, v23, vcc
	v_add_co_u32_e32 v12, vcc, s5, v22
	s_mov_b32 s5, 0x20000
	s_nop 0
	v_addc_co_u32_e32 v13, vcc, 0, v23, vcc
	global_load_dword v8, v[8:9], off
	v_readlane_b32 s41, v255, 3
	global_load_dword v19, v[12:13], off
	v_add_co_u32_e32 v12, vcc, s5, v22
	s_mov_b32 s5, 0x24000
	s_nop 0
	v_addc_co_u32_e32 v13, vcc, 0, v23, vcc
	global_load_dword v15, v[12:13], off
	v_add_co_u32_e32 v12, vcc, s5, v22
	s_mov_b32 s5, 0x28000
	s_nop 0
	v_addc_co_u32_e32 v13, vcc, 0, v23, vcc
	v_add_co_u32_e32 v24, vcc, s5, v22
	s_mov_b32 s5, 0x2c000
	s_nop 0
	v_addc_co_u32_e32 v25, vcc, 0, v23, vcc
	global_load_dword v13, v[12:13], off
	v_lshl_add_u64 v[2:3], v[2:3], 2, s[44:45]
	global_load_dword v12, v[24:25], off
	v_add_co_u32_e32 v24, vcc, s5, v22
	s_mov_b32 s5, 0x30000
	s_nop 0
	v_addc_co_u32_e32 v25, vcc, 0, v23, vcc
	global_load_dword v10, v[24:25], off
	v_add_co_u32_e32 v24, vcc, s5, v22
	v_readlane_b32 s42, v255, 4
	s_nop 0
	v_addc_co_u32_e32 v25, vcc, 0, v23, vcc
	global_load_dword v9, v[24:25], off
	v_add_co_u32_e32 v24, vcc, 0x34000, v22
	v_readlane_b32 s43, v255, 5
	s_nop 0
	v_addc_co_u32_e32 v25, vcc, 0, v23, vcc
	global_load_dword v7, v[24:25], off
	v_add_co_u32_e32 v24, vcc, 0x38000, v22
	v_readlane_b32 s52, v255, 14
	s_nop 0
	v_addc_co_u32_e32 v25, vcc, 0, v23, vcc
	v_add_co_u32_e32 v22, vcc, 0x3c000, v22
	global_load_dword v0, v[24:25], off
	s_nop 0
	v_addc_co_u32_e32 v23, vcc, 0, v23, vcc
	global_load_dword v18, v[22:23], off
	v_cndmask_b32_e64 v22, 0, 1, s[2:3]
	v_cmp_ne_u32_e64 s[40:41], 1, v22
	s_andn2_b64 vcc, exec, s[2:3]
	v_readlane_b32 s53, v255, 15
	v_readlane_b32 s54, v255, 16
	v_readlane_b32 s55, v255, 17
	s_cbranch_vccnz .LBB0_992
	global_load_dword v40, v[2:3], off
	global_load_dword v41, v[2:3], off offset:16
	global_load_dword v42, v[2:3], off offset:32
	global_load_dword v43, v[2:3], off offset:48
	global_load_dword v44, v[2:3], off offset:64
	global_load_dword v45, v[2:3], off offset:80
	global_load_dword v46, v[2:3], off offset:96
	global_load_dword v47, v[2:3], off offset:112
	global_load_dword v48, v[2:3], off offset:128
	global_load_dword v49, v[2:3], off offset:144
	global_load_dword v50, v[2:3], off offset:160
	global_load_dword v51, v[2:3], off offset:176
	global_load_dword v52, v[2:3], off offset:192
	global_load_dword v53, v[2:3], off offset:208
	global_load_dword v54, v[2:3], off offset:224
	global_load_dword v55, v[2:3], off offset:240
	s_waitcnt vmcnt(0)
	v_mul_f32_e32 v21, v21, v40
.LBB0_992:
	v_lshl_add_u32 v6, v6, 2, 0
	v_mul_lo_u32 v5, v5, s22
	v_add_u32_e32 v5, v6, v5
	s_and_b64 vcc, exec, s[40:41]
	s_waitcnt vmcnt(0)
	ds_write_b32 v5, v21
	s_cbranch_vccnz .LBB0_994
	v_mul_f32_e32 v20, v20, v41
.LBB0_994:
	s_and_b64 vcc, exec, s[40:41]
	ds_write_b32 v5, v20 offset:2064
	s_cbranch_vccnz .LBB0_996
	v_mul_f32_e32 v17, v17, v42
.LBB0_996:
	s_and_b64 vcc, exec, s[40:41]
	ds_write_b32 v5, v17 offset:4128
	s_cbranch_vccnz .LBB0_998
	v_mul_f32_e32 v16, v16, v43
.LBB0_998:
	s_and_b64 vcc, exec, s[40:41]
	ds_write_b32 v5, v16 offset:6192
	s_cbranch_vccnz .LBB0_1000
	v_mul_f32_e32 v14, v14, v44
.LBB0_1000:
	s_and_b64 vcc, exec, s[40:41]
	ds_write_b32 v5, v14 offset:8256
	s_cbranch_vccnz .LBB0_1002
	v_mul_f32_e32 v11, v11, v45
.LBB0_1002:
	s_and_b64 vcc, exec, s[40:41]
	ds_write_b32 v5, v11 offset:10320
	s_cbranch_vccnz .LBB0_1004
	v_mul_f32_e32 v8, v8, v46
.LBB0_1004:
	s_and_b64 vcc, exec, s[40:41]
	ds_write_b32 v5, v8 offset:12384
	s_cbranch_vccnz .LBB0_1006
	v_mul_f32_e32 v19, v19, v47
.LBB0_1006:
	s_and_b64 vcc, exec, s[40:41]
	ds_write_b32 v5, v19 offset:14448
	s_cbranch_vccnz .LBB0_1008
	v_mul_f32_e32 v15, v15, v48
.LBB0_1008:
	s_and_b64 vcc, exec, s[40:41]
	ds_write_b32 v5, v15 offset:16512
	s_cbranch_vccnz .LBB0_1010
	v_mul_f32_e32 v13, v13, v49
.LBB0_1010:
	s_and_b64 vcc, exec, s[40:41]
	ds_write_b32 v5, v13 offset:18576
	s_cbranch_vccnz .LBB0_1012
	v_mul_f32_e32 v12, v12, v50
.LBB0_1012:
	s_and_b64 vcc, exec, s[40:41]
	ds_write_b32 v5, v12 offset:20640
	s_cbranch_vccnz .LBB0_1014
	v_mul_f32_e32 v10, v10, v51
.LBB0_1014:
	s_and_b64 vcc, exec, s[40:41]
	ds_write_b32 v5, v10 offset:22704
	s_cbranch_vccnz .LBB0_1016
	v_mul_f32_e32 v9, v9, v52
.LBB0_1016:
	s_and_b64 vcc, exec, s[40:41]
	ds_write_b32 v5, v9 offset:24768
	s_cbranch_vccnz .LBB0_1018
	v_mul_f32_e32 v7, v7, v53
.LBB0_1018:
	s_and_b64 vcc, exec, s[40:41]
	ds_write_b32 v5, v7 offset:26832
	s_cbranch_vccnz .LBB0_1020
	v_mul_f32_e32 v0, v0, v54
.LBB0_1020:
	s_and_b64 vcc, exec, s[40:41]
	ds_write_b32 v5, v0 offset:28896
	s_cbranch_vccnz .LBB0_985
	v_mul_f32_e32 v18, v18, v55
	s_branch .LBB0_985
